# norm phases: next row's loads prefetched into spare registers before the current row's reduction/stores (counted vmcnt), on top of the up/down tile order
# speedup vs baseline: 1.0057x; 1.0057x over previous
; template <bool HIN_BF16, bool HOUT_BF16>
; __device__ __forceinline__ void norm_rows(const bf16* __restrict__ Y, const void* Hin, void* H, const float* __restrict__ gpost, float* __restrict__ RSout, int gw, int NGW, int lane) {
;     const bool blk_ = (NGW == 2048); const int m0_ = blk_ ? 2048 * ((gw >> 3) & 7) + 64 * (gw >> 6) + 8 * (gw & 7) : gw, ms_ = blk_ ? 1 : NGW, me_ = blk_ ? m0_ + 8 : SEQ;
;     for (int m = m0_; m < me_; m += ms_) {
;         f32x4 h[8];
;         if (HIN_BF16) {
; #pragma unroll
;             for (int j = 0; j < 4; ++j) { const v4u w = *(const v4u*)((const bf16*)Hin + (size_t)m * DM + 512 * j + 8 * lane);
;                 h[2 * j] = (f32x4){bf_lo(w[0]), bf_hi(w[0]), bf_lo(w[1]), bf_hi(w[1])}; h[2 * j + 1] = (f32x4){bf_lo(w[2]), bf_hi(w[2]), bf_lo(w[3]), bf_hi(w[3])}; }
;     ...
;         if (Y) {
;             v4u y[4]; float ss = 0.f;
; #pragma unroll
;             for (int j = 0; j < 4; ++j) y[j] = *(const v4u*)(Y + (size_t)m * DM + 512 * j + 8 * lane);
.LBB0_508:
.LBB0_509:
	s_cmp_le_i32 s86, s20
	s_cselect_b64 s[8:9], -1, 0
	s_and_b64 s[4:5], s[8:9], s[6:7]
	s_andn2_b64 vcc, exec, s[4:5]
	v_readlane_b32 s4, v254, 50
	v_readlane_b32 s5, v254, 51
	s_nop 1
	v_cndmask_b32_e64 v0, 0, 1, s[4:5]
	v_cmp_ne_u32_e64 s[0:1], 1, v0
	s_cbranch_vccnz .LBB0_515
	v_mov_b32_e32 v0, v230
	s_mov_b64 s[4:5], 0
	s_and_b64 vcc, exec, s[0:1]
	s_cbranch_vccnz .LBB0_515
	v_readlane_b32 s6, v255, 39
	s_add_u32 s10, s50, s4
	v_readlane_b32 s7, v255, 40
	s_addc_u32 s11, s51, s5
	s_mov_b32 s17, s7
	s_lshl_b32 s16, s74, 13
	v_writelane_b32 v255, s6, 39
	v_and_b32_e32 v32, 63, v0
	v_lshlrev_b32_e32 v204, 5, v32
	v_writelane_b32 v255, s7, 40
	s_lshl_b64 s[6:7], s[16:17], 2
	s_add_u32 s6, s10, s6
	s_addc_u32 s7, s11, s7
	v_lshl_add_u64 v[8:9], s[6:7], 0, v[204:205]
	s_mov_b64 s[6:7], 0x202000
	v_lshl_add_u64 v[10:11], v[8:9], 0, s[6:7]
	s_mov_b64 s[6:7], 0x203000
	v_lshl_add_u64 v[12:13], v[8:9], 0, s[6:7]
	s_mov_b64 s[6:7], 0x203800
	v_lshl_add_u64 v[28:29], v[8:9], 0, s[6:7]
	s_mov_b32 s6, 0x202000
	v_add_co_u32_e32 v24, vcc, s6, v8
	s_waitcnt lgkmcnt(0)
	global_load_dwordx4 v[0:3], v[10:11], off offset:16
	global_load_dwordx4 v[4:7], v[10:11], off offset:2048
	v_addc_co_u32_e32 v25, vcc, 0, v9, vcc
	v_add_co_u32_e32 v20, vcc, 0x203000, v8
	v_and_b32_e32 v33, 64, v229
	s_nop 0
	v_addc_co_u32_e32 v21, vcc, 0, v9, vcc
	global_load_dwordx4 v[8:11], v[10:11], off offset:2064
	s_nop 0
	global_load_dwordx4 v[12:15], v[12:13], off offset:16
	s_nop 0
	global_load_dwordx4 v[16:19], v[20:21], off
	s_nop 0
	global_load_dwordx4 v[20:23], v[20:21], off offset:2048
	s_nop 0
	global_load_dwordx4 v[24:27], v[24:25], off
	s_nop 0
	global_load_dwordx4 v[28:31], v[28:29], off offset:16
	v_add_u32_e32 v33, 64, v33
	v_xor_b32_e32 v34, 1, v229
	v_cmp_lt_i32_e32 vcc, v34, v33
	v_readlane_b32 s6, v255, 31
	v_lshlrev_b32_e32 v204, 4, v32
	v_cndmask_b32_e32 v34, v229, v34, vcc
	v_lshlrev_b32_e32 v36, 2, v34
	v_xor_b32_e32 v34, 2, v229
	v_cmp_lt_i32_e32 vcc, v34, v33
	v_readlane_b32 s7, v255, 32
	v_cmp_eq_u32_e64 s[42:43], 0, v32
	v_cndmask_b32_e32 v34, v229, v34, vcc
	v_lshlrev_b32_e32 v37, 2, v34
	v_xor_b32_e32 v34, 4, v229
	v_cmp_lt_i32_e32 vcc, v34, v33
	v_readlane_b32 s10, v255, 26
	s_mov_b32 s16, s10
	v_cndmask_b32_e32 v34, v229, v34, vcc
	v_lshlrev_b32_e32 v38, 2, v34
	v_xor_b32_e32 v34, 8, v229
	v_cmp_lt_i32_e32 vcc, v34, v33
	v_readlane_b32 s11, v255, 27
	s_nop 0
	v_cndmask_b32_e32 v34, v229, v34, vcc
	v_lshlrev_b32_e32 v39, 2, v34
	v_xor_b32_e32 v34, 16, v229
	v_cmp_lt_i32_e32 vcc, v34, v33
	s_nop 1
	v_cndmask_b32_e32 v34, v229, v34, vcc
	v_lshlrev_b32_e32 v40, 2, v34
	v_xor_b32_e32 v34, 32, v229
	v_cmp_lt_i32_e32 vcc, v34, v33
	s_nop 1
	v_cndmask_b32_e32 v33, v229, v34, vcc
	v_lshlrev_b32_e32 v41, 2, v33
	v_lshl_add_u64 v[32:33], s[6:7], 0, v[204:205]
	v_readlane_b32 s6, v255, 24
	v_readlane_b32 s7, v255, 25
	v_lshl_add_u64 v[192:193], v[32:33], 0, s[4:5]
	v_add_co_u32_e32 v194, vcc, s52, v192
	s_nop 1
	v_addc_co_u32_e32 v195, vcc, 0, v193, vcc
	v_add_co_u32_e32 v192, vcc, 0x39000000, v192
	s_nop 1
	v_addc_co_u32_e32 v193, vcc, 0, v193, vcc
	global_load_dwordx4 v[160:163], v[194:195], off
	global_load_dwordx4 v[164:167], v[194:195], off offset:1024
	global_load_dwordx4 v[168:171], v[194:195], off offset:2048
	global_load_dwordx4 v[172:175], v[194:195], off offset:3072
	global_load_dwordx4 v[176:179], v[192:193], off
	global_load_dwordx4 v[180:183], v[192:193], off offset:1024
	global_load_dwordx4 v[184:187], v[192:193], off offset:2048
	global_load_dwordx4 v[188:191], v[192:193], off offset:3072
	s_waitcnt vmcnt(0)
	s_branch .LBB0_513

; template <bool HIN_BF16, bool HOUT_BF16>
; __device__ __forceinline__ void norm_rows(const bf16* __restrict__ Y, const void* Hin, void* H, const float* __restrict__ gpost, float* __restrict__ RSout, int gw, int NGW, int lane) {
;     ...
;     for (int m = m0_; m < me_; m += ms_) {
;         f32x4 h[8];
;         if (HIN_BF16) {
; #pragma unroll
;             for (int j = 0; j < 4; ++j) { const v4u w = *(const v4u*)((const bf16*)Hin + (size_t)m * DM + 512 * j + 8 * lane);
;                 h[2 * j] = (f32x4){bf_lo(w[0]), bf_hi(w[0]), bf_lo(w[1]), bf_hi(w[1])}; h[2 * j + 1] = (f32x4){bf_lo(w[2]), bf_hi(w[2]), bf_lo(w[3]), bf_hi(w[3])}; }
;         } else {
;             const float* hr = (const float*)Hin + (size_t)m * DM + 8 * lane;
; #pragma unroll
;             for (int j = 0; j < 4; ++j) { h[2 * j] = *(const f32x4*)(hr + 512 * j); h[2 * j + 1] = *(const f32x4*)(hr + 512 * j + 4); }
;         }
;         if (Y) {
;             v4u y[4]; float ss = 0.f;
; #pragma unroll
;             for (int j = 0; j < 4; ++j) y[j] = *(const v4u*)(Y + (size_t)m * DM + 512 * j + 8 * lane);
; #pragma unroll
;             for (int j = 0; j < 4; ++j)
; #pragma unroll
;                 for (int e = 0; e < 4; ++e) { const float a = bf_lo(y[j][e]), b = bf_hi(y[j][e]); ss += a * a + b * b; }
;             const float rs = 1.0f / sqrtf(wave_sum(ss) * (1.0f / DM) + RMS_EPS);
.LBB0_513:
	v_lshl_add_u64 v[34:35], v[32:33], 0, s[4:5]
	v_add_co_u32_e32 v34, vcc, 0x39000000, v34
	s_nop 1
	v_addc_co_u32_e32 v35, vcc, 0, v35, vcc
	s_waitcnt lgkmcnt(0)
	s_waitcnt vmcnt(4)
	v_mov_b64_e32 v[42:43], v[160:161]
	v_mov_b64_e32 v[44:45], v[162:163]
	v_mov_b64_e32 v[46:47], v[164:165]
	v_mov_b64_e32 v[48:49], v[166:167]
	v_mov_b64_e32 v[50:51], v[168:169]
	v_mov_b64_e32 v[52:53], v[170:171]
	v_mov_b64_e32 v[54:55], v[172:173]
	v_mov_b64_e32 v[56:57], v[174:175]
	v_mov_b64_e32 v[58:59], v[176:177]
	v_mov_b64_e32 v[60:61], v[178:179]
	v_mov_b64_e32 v[62:63], v[180:181]
	v_mov_b64_e32 v[64:65], v[182:183]
	v_mov_b64_e32 v[66:67], v[184:185]
	v_mov_b64_e32 v[68:69], v[186:187]
	v_mov_b64_e32 v[70:71], v[188:189]
	v_mov_b64_e32 v[72:73], v[190:191]
	s_add_i32 s20, s16, s80
	s_cmp_lt_i32 s20, s96
	s_cbranch_scc0 .Ln1_nopf
	v_lshl_add_u64 v[192:193], v[32:33], 0, s[18:19]
	v_lshl_add_u64 v[192:193], v[192:193], 0, s[4:5]
	v_add_co_u32_e32 v194, vcc, s52, v192
	s_nop 1
	v_addc_co_u32_e32 v195, vcc, 0, v193, vcc
	v_add_co_u32_e32 v192, vcc, 0x39000000, v192
	s_nop 1
	v_addc_co_u32_e32 v193, vcc, 0, v193, vcc
	global_load_dwordx4 v[160:163], v[194:195], off
	global_load_dwordx4 v[164:167], v[194:195], off offset:1024
	global_load_dwordx4 v[168:171], v[194:195], off offset:2048
	global_load_dwordx4 v[172:175], v[194:195], off offset:3072
	global_load_dwordx4 v[176:179], v[192:193], off
	global_load_dwordx4 v[180:183], v[192:193], off offset:1024
	global_load_dwordx4 v[184:187], v[192:193], off offset:2048
	global_load_dwordx4 v[188:191], v[192:193], off offset:3072
.Ln1_nopf:
	v_lshlrev_b32_e32 v74, 16, v42
	v_and_b32_e32 v75, 0xffff0000, v42
	v_lshlrev_b32_e32 v42, 16, v43
	v_and_b32_e32 v43, 0xffff0000, v43
	v_and_b32_e32 v77, 0xffff0000, v44
	v_lshlrev_b32_e32 v90, 16, v58
	v_and_b32_e32 v91, 0xffff0000, v58
	v_mul_f32_e32 v58, v75, v75
	v_mul_f32_e32 v94, v43, v43
	v_lshlrev_b32_e32 v76, 16, v44
	v_lshlrev_b32_e32 v44, 16, v45
	v_and_b32_e32 v45, 0xffff0000, v45
	v_mul_f32_e32 v95, v77, v77
	v_fmac_f32_e32 v58, v74, v74
	v_fmac_f32_e32 v94, v42, v42
	v_and_b32_e32 v79, 0xffff0000, v46
	v_mul_f32_e32 v96, v45, v45
	v_fmac_f32_e32 v95, v76, v76
	v_add_f32_e32 v58, v58, v94
	v_lshlrev_b32_e32 v78, 16, v46
	v_lshlrev_b32_e32 v46, 16, v47
	v_and_b32_e32 v47, 0xffff0000, v47
	v_mul_f32_e32 v97, v79, v79
	v_fmac_f32_e32 v96, v44, v44
	v_add_f32_e32 v58, v95, v58
	v_and_b32_e32 v81, 0xffff0000, v48
	v_mul_f32_e32 v98, v47, v47
	v_fmac_f32_e32 v97, v78, v78
	v_add_f32_e32 v58, v96, v58
	v_lshlrev_b32_e32 v80, 16, v48
	v_lshlrev_b32_e32 v48, 16, v49
	v_and_b32_e32 v49, 0xffff0000, v49
	v_mul_f32_e32 v99, v81, v81
	v_fmac_f32_e32 v98, v46, v46
	v_add_f32_e32 v58, v97, v58
	v_and_b32_e32 v83, 0xffff0000, v50
	v_mul_f32_e32 v100, v49, v49
	v_fmac_f32_e32 v99, v80, v80
	v_add_f32_e32 v58, v98, v58
	v_lshlrev_b32_e32 v82, 16, v50
	v_lshlrev_b32_e32 v50, 16, v51
	v_and_b32_e32 v51, 0xffff0000, v51
	v_mul_f32_e32 v101, v83, v83
	v_fmac_f32_e32 v100, v48, v48
	v_add_f32_e32 v58, v99, v58
	v_and_b32_e32 v85, 0xffff0000, v52
	v_mul_f32_e32 v102, v51, v51
	v_fmac_f32_e32 v101, v82, v82
	v_add_f32_e32 v58, v100, v58
	v_lshlrev_b32_e32 v84, 16, v52
	v_lshlrev_b32_e32 v52, 16, v53
	v_and_b32_e32 v53, 0xffff0000, v53
	v_mul_f32_e32 v103, v85, v85
	v_fmac_f32_e32 v102, v50, v50
	v_add_f32_e32 v58, v101, v58
	v_and_b32_e32 v87, 0xffff0000, v54
	v_mul_f32_e32 v104, v53, v53
	v_fmac_f32_e32 v103, v84, v84
	v_add_f32_e32 v58, v102, v58
	v_lshlrev_b32_e32 v86, 16, v54
	v_lshlrev_b32_e32 v54, 16, v55
	v_and_b32_e32 v55, 0xffff0000, v55
	v_mul_f32_e32 v105, v87, v87
	v_fmac_f32_e32 v104, v52, v52
	v_add_f32_e32 v58, v103, v58
	v_lshlrev_b32_e32 v89, 16, v57
	v_lshlrev_b32_e32 v88, 16, v56
	v_and_b32_e32 v57, 0xffff0000, v57
	v_and_b32_e32 v56, 0xffff0000, v56
	v_mul_f32_e32 v106, v55, v55
	v_fmac_f32_e32 v105, v86, v86
	v_add_f32_e32 v58, v104, v58
	v_pk_mul_f32 v[92:93], v[56:57], v[56:57]
	v_fmac_f32_e32 v106, v54, v54
	v_add_f32_e32 v58, v105, v58
	v_pk_fma_f32 v[92:93], v[88:89], v[88:89], v[92:93]
	v_add_f32_e32 v58, v106, v58
	v_add_f32_e32 v58, v92, v58
	v_add_f32_e32 v94, v93, v58
	ds_bpermute_b32 v95, v36, v94
	v_lshlrev_b32_e32 v58, 16, v59
	v_and_b32_e32 v59, 0xffff0000, v59
	v_pk_mul_f32 v[42:43], v[26:27], v[42:43]
	v_lshlrev_b32_e32 v92, 16, v60
	s_waitcnt lgkmcnt(0)
	v_add_f32_e32 v96, v94, v95
	ds_bpermute_b32 v97, v37, v96
	v_and_b32_e32 v93, 0xffff0000, v60
	v_lshlrev_b32_e32 v60, 16, v61
	v_and_b32_e32 v61, 0xffff0000, v61
	v_pk_mul_f32 v[44:45], v[2:3], v[44:45]
	s_waitcnt lgkmcnt(0)
	v_add_f32_e32 v98, v96, v97
	ds_bpermute_b32 v99, v38, v98
	v_lshlrev_b32_e32 v94, 16, v62
	v_and_b32_e32 v95, 0xffff0000, v62
	v_lshlrev_b32_e32 v62, 16, v63
	v_and_b32_e32 v63, 0xffff0000, v63
	s_waitcnt lgkmcnt(0)
	v_add_f32_e32 v100, v98, v99
	ds_bpermute_b32 v101, v39, v100
	v_lshlrev_b32_e32 v96, 16, v64
	v_and_b32_e32 v97, 0xffff0000, v64
	v_lshlrev_b32_e32 v64, 16, v65
	v_and_b32_e32 v65, 0xffff0000, v65
	s_waitcnt lgkmcnt(0)
	v_add_f32_e32 v102, v100, v101
	ds_bpermute_b32 v103, v40, v102
	v_lshlrev_b32_e32 v98, 16, v66
	v_and_b32_e32 v99, 0xffff0000, v66
	v_lshlrev_b32_e32 v66, 16, v67
	v_and_b32_e32 v67, 0xffff0000, v67
	s_waitcnt lgkmcnt(0)
	v_add_f32_e32 v104, v102, v103
	ds_bpermute_b32 v105, v41, v104
	v_lshlrev_b32_e32 v102, 16, v70
	v_and_b32_e32 v103, 0xffff0000, v70
	v_lshlrev_b32_e32 v100, 16, v68
	v_and_b32_e32 v101, 0xffff0000, v68
	s_waitcnt lgkmcnt(0)
; __device__ __forceinline__ unsigned pk2(float lo, float hi) { return f2bf(lo) | (f2bf(hi) << 16); }
; template <bool HIN_BF16, bool HOUT_BF16>
; __device__ __forceinline__ void norm_rows(const bf16* __restrict__ Y, const void* Hin, void* H, const float* __restrict__ gpost, float* __restrict__ RSout, int gw, int NGW, int lane) {
;     ...
;             const float rs = 1.0f / sqrtf(wave_sum(ss) * (1.0f / DM) + RMS_EPS);
; #pragma unroll
;             for (int j = 0; j < 4; ++j) { const f32x4 g0 = *(const f32x4*)(gpost + 512 * j + 8 * lane), g1 = *(const f32x4*)(gpost + 512 * j + 8 * lane + 4);
;                 f32x4 a = {bf_lo(y[j][0]), bf_hi(y[j][0]), bf_lo(y[j][1]), bf_hi(y[j][1])}, b = {bf_lo(y[j][2]), bf_hi(y[j][2]), bf_lo(y[j][3]), bf_hi(y[j][3])};
;                 h[2 * j] = h[2 * j] + a * g0 * rs; h[2 * j + 1] = h[2 * j + 1] + b * g1 * rs; }
;         }
;         if (HOUT_BF16) {
; #pragma unroll
;             for (int j = 0; j < 4; ++j) { v4u w; w.x = pk2(h[2 * j][0], h[2 * j][1]); w.y = pk2(h[2 * j][2], h[2 * j][3]); w.z = pk2(h[2 * j + 1][0], h[2 * j + 1][1]); w.w = pk2(h[2 * j + 1][2], h[2 * j + 1][3]);
;                 *(v4u*)((bf16*)H + (size_t)m * DM + 512 * j + 8 * lane) = w; }
	v_add_f32_e32 v70, v104, v105
	v_fmamk_f32 v70, v70, 0x3a000000, v226
	v_mul_f32_e32 v104, 0x4f800000, v70
	v_cmp_gt_f32_e32 vcc, s93, v70
	v_lshlrev_b32_e32 v68, 16, v69
	v_and_b32_e32 v69, 0xffff0000, v69
	v_cndmask_b32_e32 v105, v70, v104, vcc
	v_sqrt_f32_e32 v106, v105
	v_lshlrev_b32_e32 v70, 16, v71
	v_and_b32_e32 v71, 0xffff0000, v71
	v_pk_mul_f32 v[74:75], v[24:25], v[74:75]
	v_add_u32_e32 v107, -1, v106
	v_fma_f32 v109, -v107, v106, v105
	v_add_u32_e32 v108, 1, v106
	v_cmp_ge_f32_e64 s[46:47], 0, v109
	v_lshlrev_b32_e32 v104, 16, v72
	s_nop 0
	v_cndmask_b32_e64 v107, v106, v107, s[46:47]
	v_fma_f32 v106, -v108, v106, v105
	v_cmp_lt_f32_e64 s[46:47], 0, v106
	s_nop 1
	v_cndmask_b32_e64 v106, v107, v108, s[46:47]
	v_mul_f32_e32 v107, 0x37800000, v106
	v_cndmask_b32_e32 v106, v106, v107, vcc
	v_cmp_class_f32_e32 vcc, v105, v227
	s_nop 1
	v_cndmask_b32_e32 v106, v106, v105, vcc
	v_div_scale_f32 v107, s[10:11], v106, v106, 1.0
	v_rcp_f32_e32 v108, v107
	v_and_b32_e32 v105, 0xffff0000, v72
	v_lshlrev_b32_e32 v72, 16, v73
	v_and_b32_e32 v73, 0xffff0000, v73
	v_fma_f32 v109, -v107, v108, 1.0
	v_fmac_f32_e32 v108, v109, v108
	v_div_scale_f32 v109, vcc, 1.0, v106, 1.0
	v_mul_f32_e32 v110, v109, v108
	v_fma_f32 v111, -v107, v110, v109
	v_fmac_f32_e32 v110, v111, v108
	v_fma_f32 v107, -v107, v110, v109
	v_div_fmas_f32 v107, v107, v108, v110
	v_div_fixup_f32 v106, v107, v106, 1.0
	v_pk_fma_f32 v[58:59], v[42:43], v[106:107], v[58:59] op_sel_hi:[1,0,1]
	v_pk_mul_f32 v[42:43], v[0:1], v[76:77]
	v_pk_fma_f32 v[60:61], v[44:45], v[106:107], v[60:61] op_sel_hi:[1,0,1]
	v_pk_fma_f32 v[76:77], v[42:43], v[106:107], v[92:93] op_sel_hi:[1,0,1]
	v_pk_mul_f32 v[42:43], v[4:5], v[78:79]
	v_pk_mul_f32 v[44:45], v[6:7], v[46:47]
	v_pk_fma_f32 v[74:75], v[74:75], v[106:107], v[90:91] op_sel_hi:[1,0,1]
	v_pk_fma_f32 v[46:47], v[44:45], v[106:107], v[62:63] op_sel_hi:[1,0,1]
	v_pk_fma_f32 v[62:63], v[42:43], v[106:107], v[94:95] op_sel_hi:[1,0,1]
	v_pk_mul_f32 v[42:43], v[8:9], v[80:81]
	v_pk_mul_f32 v[44:45], v[10:11], v[48:49]
	v_bfe_u32 v78, v61, 16, 1
	v_pk_fma_f32 v[48:49], v[44:45], v[106:107], v[64:65] op_sel_hi:[1,0,1]
	v_pk_fma_f32 v[64:65], v[42:43], v[106:107], v[96:97] op_sel_hi:[1,0,1]
	v_pk_mul_f32 v[42:43], v[16:17], v[82:83]
	v_pk_mul_f32 v[44:45], v[18:19], v[50:51]
	v_add3_u32 v78, v61, v78, s56
	v_pk_fma_f32 v[50:51], v[44:45], v[106:107], v[66:67] op_sel_hi:[1,0,1]
	v_pk_fma_f32 v[66:67], v[42:43], v[106:107], v[98:99] op_sel_hi:[1,0,1]
	v_pk_mul_f32 v[42:43], v[12:13], v[84:85]
	v_pk_mul_f32 v[44:45], v[14:15], v[52:53]
	s_nop 0
	v_pk_fma_f32 v[52:53], v[44:45], v[106:107], v[68:69] op_sel_hi:[1,0,1]
	v_pk_fma_f32 v[68:69], v[42:43], v[106:107], v[100:101] op_sel_hi:[1,0,1]
	v_pk_mul_f32 v[42:43], v[20:21], v[86:87]
	v_pk_mul_f32 v[44:45], v[22:23], v[54:55]
	s_nop 0
	v_pk_fma_f32 v[54:55], v[44:45], v[106:107], v[70:71] op_sel_hi:[1,0,1]
	v_pk_fma_f32 v[70:71], v[42:43], v[106:107], v[102:103] op_sel_hi:[1,0,1]
	v_mov_b32_e32 v42, v88
	v_mov_b32_e32 v43, v56
	v_mov_b32_e32 v56, v89
	v_pk_mul_f32 v[42:43], v[28:29], v[42:43]
	v_pk_mul_f32 v[44:45], v[30:31], v[56:57]
	s_nop 0
	v_pk_fma_f32 v[56:57], v[44:45], v[106:107], v[72:73] op_sel_hi:[1,0,1]
	v_pk_fma_f32 v[72:73], v[42:43], v[106:107], v[104:105] op_sel_hi:[1,0,1]
	v_bfe_u32 v42, v74, 16, 1
	v_add3_u32 v42, v74, v42, s56
	v_bfe_u32 v43, v75, 16, 1
	v_lshrrev_b32_e32 v42, 16, v42
	v_add3_u32 v43, v75, v43, s56
	v_and_or_b32 v42, v43, s82, v42
	v_bfe_u32 v43, v58, 16, 1
	v_add3_u32 v43, v58, v43, s56
	v_bfe_u32 v44, v59, 16, 1
	v_lshrrev_b32_e32 v43, 16, v43
	v_add3_u32 v44, v59, v44, s56
	v_and_or_b32 v43, v44, s82, v43
	v_bfe_u32 v44, v76, 16, 1
	v_add3_u32 v44, v76, v44, s56
	v_bfe_u32 v45, v77, 16, 1
	v_lshrrev_b32_e32 v44, 16, v44
	v_add3_u32 v45, v77, v45, s56
	v_and_or_b32 v44, v45, s82, v44
	v_bfe_u32 v45, v60, 16, 1
	v_add3_u32 v45, v60, v45, s56
	v_lshrrev_b32_e32 v45, 16, v45
	v_and_or_b32 v45, v78, s82, v45
	global_store_dwordx4 v[34:35], v[42:45], off
	v_bfe_u32 v78, v49, 16, 1
	v_add3_u32 v78, v49, v78, s56
	v_bfe_u32 v42, v62, 16, 1
	v_add3_u32 v42, v62, v42, s56
	v_bfe_u32 v43, v63, 16, 1
	v_lshrrev_b32_e32 v42, 16, v42
	v_add3_u32 v43, v63, v43, s56
	v_and_or_b32 v42, v43, s82, v42
	v_bfe_u32 v43, v46, 16, 1
	v_add3_u32 v43, v46, v43, s56
	v_bfe_u32 v44, v47, 16, 1
	v_lshrrev_b32_e32 v43, 16, v43
	v_add3_u32 v44, v47, v44, s56
	v_and_or_b32 v43, v44, s82, v43
	v_bfe_u32 v44, v64, 16, 1
	v_add3_u32 v44, v64, v44, s56
	v_bfe_u32 v45, v65, 16, 1
	v_lshrrev_b32_e32 v44, 16, v44
	v_add3_u32 v45, v65, v45, s56
	v_and_or_b32 v44, v45, s82, v44
	v_bfe_u32 v45, v48, 16, 1
	v_add3_u32 v45, v48, v45, s56
	v_lshrrev_b32_e32 v45, 16, v45
; __device__ __forceinline__ unsigned pk2(float lo, float hi) { return f2bf(lo) | (f2bf(hi) << 16); }
; template <bool HIN_BF16, bool HOUT_BF16>
; __device__ __forceinline__ void norm_rows(const bf16* __restrict__ Y, const void* Hin, void* H, const float* __restrict__ gpost, float* __restrict__ RSout, int gw, int NGW, int lane) {
;     ...
;         if (HOUT_BF16) {
; #pragma unroll
;             for (int j = 0; j < 4; ++j) { v4u w; w.x = pk2(h[2 * j][0], h[2 * j][1]); w.y = pk2(h[2 * j][2], h[2 * j][3]); w.z = pk2(h[2 * j + 1][0], h[2 * j + 1][1]); w.w = pk2(h[2 * j + 1][2], h[2 * j + 1][3]);
;                 *(v4u*)((bf16*)H + (size_t)m * DM + 512 * j + 8 * lane) = w; }
;         } else { float* ho = (float*)H + (size_t)m * DM + 8 * lane;
; #pragma unroll
;             for (int j = 0; j < 4; ++j) { *(f32x4*)(ho + 512 * j) = h[2 * j]; *(f32x4*)(ho + 512 * j + 4) = h[2 * j + 1]; } }
;         if (RSout) {
;             float ss = 0.f;
; #pragma unroll
;             for (int j = 0; j < 8; ++j) ss += (h[j][0] * h[j][0] + h[j][1] * h[j][1]) + (h[j][2] * h[j][2] + h[j][3] * h[j][3]);
;             const float rs = 1.0f / sqrtf(wave_sum(ss) * (1.0f / DM) + RMS_EPS);
;             if (lane == 0) RSout[m] = rs;
;         }
	v_and_or_b32 v45, v78, s82, v45
	global_store_dwordx4 v[34:35], v[42:45], off offset:1024
	v_bfe_u32 v78, v53, 16, 1
	v_add3_u32 v78, v53, v78, s56
	v_bfe_u32 v42, v66, 16, 1
	v_add3_u32 v42, v66, v42, s56
	v_bfe_u32 v43, v67, 16, 1
	v_lshrrev_b32_e32 v42, 16, v42
	v_add3_u32 v43, v67, v43, s56
	v_and_or_b32 v42, v43, s82, v42
	v_bfe_u32 v43, v50, 16, 1
	v_add3_u32 v43, v50, v43, s56
	v_bfe_u32 v44, v51, 16, 1
	v_lshrrev_b32_e32 v43, 16, v43
	v_add3_u32 v44, v51, v44, s56
	v_and_or_b32 v43, v44, s82, v43
	v_bfe_u32 v44, v68, 16, 1
	v_add3_u32 v44, v68, v44, s56
	v_bfe_u32 v45, v69, 16, 1
	v_lshrrev_b32_e32 v44, 16, v44
	v_add3_u32 v45, v69, v45, s56
	v_and_or_b32 v44, v45, s82, v44
	v_bfe_u32 v45, v52, 16, 1
	v_add3_u32 v45, v52, v45, s56
	v_lshrrev_b32_e32 v45, 16, v45
	v_and_or_b32 v45, v78, s82, v45
	global_store_dwordx4 v[34:35], v[42:45], off offset:2048
	s_nop 1
	v_mul_f32_e32 v43, v75, v75
	v_mul_f32_e32 v44, v59, v59
	v_fmac_f32_e32 v43, v74, v74
	v_fmac_f32_e32 v44, v58, v58
	v_add_f32_e32 v43, v43, v44
	v_mul_f32_e32 v44, v77, v77
	v_mul_f32_e32 v45, v61, v61
	v_fmac_f32_e32 v44, v76, v76
	v_fmac_f32_e32 v45, v60, v60
	v_add_f32_e32 v44, v44, v45
	v_add_f32_e32 v43, v43, v44
	v_mul_f32_e32 v44, v63, v63
	v_mul_f32_e32 v45, v47, v47
	v_fmac_f32_e32 v44, v62, v62
	v_fmac_f32_e32 v45, v46, v46
	v_add_f32_e32 v44, v44, v45
	v_add_f32_e32 v43, v44, v43
	v_mul_f32_e32 v44, v65, v65
	v_mul_f32_e32 v45, v49, v49
	v_fmac_f32_e32 v44, v64, v64
	v_fmac_f32_e32 v45, v48, v48
	v_add_f32_e32 v44, v44, v45
	v_add_f32_e32 v43, v44, v43
	v_mul_f32_e32 v44, v67, v67
	v_mul_f32_e32 v45, v51, v51
	v_fmac_f32_e32 v44, v66, v66
	v_fmac_f32_e32 v45, v50, v50
	v_add_f32_e32 v44, v44, v45
	v_add_f32_e32 v43, v44, v43
	v_mul_f32_e32 v44, v69, v69
	v_mul_f32_e32 v45, v53, v53
	v_fmac_f32_e32 v44, v68, v68
	v_fmac_f32_e32 v45, v52, v52
	v_add_f32_e32 v44, v44, v45
	v_add_f32_e32 v43, v44, v43
	v_mul_f32_e32 v44, v71, v71
	v_mul_f32_e32 v45, v55, v55
	v_fmac_f32_e32 v44, v70, v70
	v_fmac_f32_e32 v45, v54, v54
	v_add_f32_e32 v44, v44, v45
	v_add_f32_e32 v43, v44, v43
	v_mul_f32_e32 v44, v73, v73
	v_mul_f32_e32 v45, v57, v57
	v_fmac_f32_e32 v44, v72, v72
	v_fmac_f32_e32 v45, v56, v56
	v_add_f32_e32 v44, v44, v45
	v_add_f32_e32 v43, v44, v43
	ds_bpermute_b32 v44, v36, v43
	v_bfe_u32 v42, v70, 16, 1
	v_add3_u32 v42, v70, v42, s56
	v_bfe_u32 v45, v71, 16, 1
	v_lshrrev_b32_e32 v42, 16, v42
	s_waitcnt lgkmcnt(0)
	v_add_f32_e32 v43, v43, v44
	ds_bpermute_b32 v46, v37, v43
	v_add3_u32 v45, v71, v45, s56
	v_and_or_b32 v44, v45, s82, v42
	v_bfe_u32 v42, v54, 16, 1
	v_add3_u32 v42, v54, v42, s56
	s_waitcnt lgkmcnt(0)
	v_add_f32_e32 v43, v43, v46
	ds_bpermute_b32 v46, v38, v43
	v_bfe_u32 v45, v55, 16, 1
	v_lshrrev_b32_e32 v42, 16, v42
	v_add3_u32 v45, v55, v45, s56
	v_and_or_b32 v45, v45, s82, v42
	s_waitcnt lgkmcnt(0)
	v_add_f32_e32 v43, v43, v46
	ds_bpermute_b32 v46, v39, v43
	v_bfe_u32 v42, v72, 16, 1
	v_add3_u32 v42, v72, v42, s56
	v_bfe_u32 v47, v73, 16, 1
	v_lshrrev_b32_e32 v42, 16, v42
	s_waitcnt lgkmcnt(0)
	v_add_f32_e32 v43, v43, v46
	ds_bpermute_b32 v48, v40, v43
	v_add3_u32 v47, v73, v47, s56
	v_and_or_b32 v46, v47, s82, v42
	v_bfe_u32 v42, v56, 16, 1
	v_add3_u32 v42, v56, v42, s56
	v_lshrrev_b32_e32 v47, 16, v42
	s_waitcnt lgkmcnt(0)
	v_add_f32_e32 v42, v43, v48
	ds_bpermute_b32 v43, v41, v42
	v_bfe_u32 v48, v57, 16, 1
	v_add3_u32 v48, v57, v48, s56
	v_and_or_b32 v47, v48, s82, v47
	global_store_dwordx4 v[34:35], v[44:47], off offset:3072
	s_and_saveexec_b64 s[10:11], s[42:43]
	s_cbranch_execz .LBB0_512
	s_waitcnt lgkmcnt(0)
	v_add_f32_e32 v34, v42, v43
	v_fmamk_f32 v34, v34, 0x3a000000, v226
	v_mul_f32_e32 v35, 0x4f800000, v34
	v_cmp_gt_f32_e32 vcc, s93, v34
	s_nop 1
	v_cndmask_b32_e32 v34, v34, v35, vcc
	v_sqrt_f32_e32 v35, v34
	s_nop 0
	v_add_u32_e32 v42, -1, v35
	v_fma_f32 v44, -v42, v35, v34
	v_add_u32_e32 v43, 1, v35
	v_cmp_ge_f32_e64 s[46:47], 0, v44
	s_nop 1
	v_cndmask_b32_e64 v42, v35, v42, s[46:47]
	v_fma_f32 v35, -v43, v35, v34
	v_cmp_lt_f32_e64 s[46:47], 0, v35
	s_nop 1
	v_cndmask_b32_e64 v35, v42, v43, s[46:47]
	v_mul_f32_e32 v42, 0x37800000, v35
	v_cndmask_b32_e32 v35, v35, v42, vcc
	v_cmp_class_f32_e32 vcc, v34, v227
	s_nop 1
	v_cndmask_b32_e32 v34, v35, v34, vcc
	v_div_scale_f32 v35, s[20:21], v34, v34, 1.0
	v_rcp_f32_e32 v42, v35
	s_add_u32 s20, s6, s4
	s_addc_u32 s21, s7, s5
	v_fma_f32 v43, -v35, v42, 1.0
	v_fmac_f32_e32 v42, v43, v42
	v_div_scale_f32 v43, vcc, 1.0, v34, 1.0
	v_mul_f32_e32 v44, v43, v42
	v_fma_f32 v45, -v35, v44, v43
	v_fmac_f32_e32 v44, v45, v42
	v_fma_f32 v35, -v35, v44, v43
	v_div_fmas_f32 v35, v35, v42, v44
	v_div_fixup_f32 v34, v35, v34, 1.0
	global_store_dword v205, v34, s[20:21]
	s_branch .LBB0_512

; #define FRESH_TID() int tid = threadIdx.x; asm volatile("" : "+v"(tid)); const int lane = tid & 63
; template <bool HIN_BF16, bool HOUT_BF16>
; __device__ __forceinline__ void norm_rows(const bf16* __restrict__ Y, const void* Hin, void* H, const float* __restrict__ gpost, float* __restrict__ RSout, int gw, int NGW, int lane) {
;     const bool blk_ = (NGW == 2048); const int m0_ = blk_ ? 2048 * ((gw >> 3) & 7) + 64 * (gw >> 6) + 8 * (gw & 7) : gw, ms_ = blk_ ? 1 : NGW, me_ = blk_ ? m0_ + 8 : SEQ;
;     for (int m = m0_; m < me_; m += ms_) {
;         f32x4 h[8];
;         if (HIN_BF16) {
; #pragma unroll
;             for (int j = 0; j < 4; ++j) { const v4u w = *(const v4u*)((const bf16*)Hin + (size_t)m * DM + 512 * j + 8 * lane);
;                 h[2 * j] = (f32x4){bf_lo(w[0]), bf_hi(w[0]), bf_lo(w[1]), bf_hi(w[1])}; h[2 * j + 1] = (f32x4){bf_lo(w[2]), bf_hi(w[2]), bf_lo(w[3]), bf_hi(w[3])}; }
;         } else {
;             const float* hr = (const float*)Hin + (size_t)m * DM + 8 * lane;
; #pragma unroll
;             for (int j = 0; j < 4; ++j) { h[2 * j] = *(const f32x4*)(hr + 512 * j); h[2 * j + 1] = *(const f32x4*)(hr + 512 * j + 4); }
;         }
;         if (Y) {
;             v4u y[4]; float ss = 0.f;
; #pragma unroll
;             for (int j = 0; j < 4; ++j) y[j] = *(const v4u*)(Y + (size_t)m * DM + 512 * j + 8 * lane);
; #pragma unroll
;             for (int j = 0; j < 4; ++j)
; #pragma unroll
;                 for (int e = 0; e < 4; ++e) { const float a = bf_lo(y[j][e]), b = bf_hi(y[j][e]); ss += a * a + b * b; }
;             const float rs = 1.0f / sqrtf(wave_sum(ss) * (1.0f / DM) + RMS_EPS);
; #pragma unroll
;             for (int j = 0; j < 4; ++j) { const f32x4 g0 = *(const f32x4*)(gpost + 512 * j + 8 * lane), g1 = *(const f32x4*)(gpost + 512 * j + 8 * lane + 4);
; __global__ void __launch_bounds__(512, 2) trunk_fwd(Args a) {
;     ...
;         if (RUN()) { FRESH_TID(); (void)tid; FRESH_WS(); const float* gL = normg + (size_t)L * 4 * DM; if (L + 1 < DEPTH) norm_rows<true, true>(YB, ws + WS_HB, ws + WS_HB, gL + 3 * DM, (float*)(ws + WS_RS), gw, NGW, lane);
;             else norm_rows<true, false>(YB, ws + WS_HB, a.out, gL + 3 * DM, nullptr, gw, NGW, lane); }
.LBB0_786:
	s_cmp_le_i32 s86, s36
	s_cselect_b64 s[46:47], -1, 0
	s_and_b64 s[4:5], s[46:47], s[6:7]
	v_readlane_b32 s22, v255, 43
	s_andn2_b64 vcc, exec, s[4:5]
	v_readlane_b32 s23, v255, 44
	s_cbranch_vccnz .LBB0_798
	v_mov_b32_e32 v0, v230
	s_mov_b64 s[4:5], 0
	v_readlane_b32 s6, v255, 39
	s_add_u32 s8, s50, s4
	v_readlane_b32 s7, v255, 40
	s_addc_u32 s9, s51, s5
	s_mov_b32 s11, s7
	s_lshl_b32 s10, s74, 13
	v_writelane_b32 v255, s6, 39
	v_and_b32_e32 v36, 63, v0
	s_nop 0
	v_writelane_b32 v255, s7, 40
	s_lshl_b64 s[6:7], s[10:11], 2
	s_add_u32 s6, s8, s6
	s_addc_u32 s7, s9, s7
	s_add_u32 s6, s6, 0x200000
	s_addc_u32 s7, s7, 0
	s_cmp_eq_u32 s74, 3
	s_mov_b64 s[8:9], -1
	s_cbranch_scc1 .LBB0_794
	s_and_b64 vcc, exec, s[0:1]
	s_cbranch_vccnz .LBB0_793
	v_lshlrev_b32_e32 v204, 5, v36
	v_lshl_add_u64 v[8:9], s[6:7], 0, v[204:205]
	s_mov_b64 s[8:9], 0x6000
	v_lshl_add_u64 v[10:11], v[8:9], 0, s[8:9]
	s_mov_b64 s[8:9], 0x7000
	v_lshl_add_u64 v[12:13], v[8:9], 0, s[8:9]
	s_mov_b64 s[8:9], 0x7800
	v_lshl_add_u64 v[28:29], v[8:9], 0, s[8:9]
	s_movk_i32 s8, 0x6000
	v_add_co_u32_e32 v24, vcc, s8, v8
	s_waitcnt lgkmcnt(0)
	global_load_dwordx4 v[0:3], v[10:11], off offset:16
	global_load_dwordx4 v[4:7], v[10:11], off offset:2048
	v_addc_co_u32_e32 v25, vcc, 0, v9, vcc
	v_add_co_u32_e32 v20, vcc, 0x7000, v8
	v_and_b32_e32 v32, 64, v229
	s_nop 0
	v_addc_co_u32_e32 v21, vcc, 0, v9, vcc
	global_load_dwordx4 v[8:11], v[10:11], off offset:2064
	s_nop 0
	global_load_dwordx4 v[12:15], v[12:13], off offset:16
	s_nop 0
	global_load_dwordx4 v[16:19], v[20:21], off
	s_nop 0
	global_load_dwordx4 v[20:23], v[20:21], off offset:2048
	s_nop 0
	global_load_dwordx4 v[24:27], v[24:25], off
	s_nop 0
	global_load_dwordx4 v[28:31], v[28:29], off offset:16
	v_add_u32_e32 v32, 64, v32
	v_xor_b32_e32 v33, 1, v229
	v_cmp_lt_i32_e32 vcc, v33, v32
	v_readlane_b32 s8, v255, 31
	v_lshlrev_b32_e32 v204, 4, v36
	v_cndmask_b32_e32 v33, v229, v33, vcc
	v_lshlrev_b32_e32 v37, 2, v33
	v_xor_b32_e32 v33, 2, v229
	v_cmp_lt_i32_e32 vcc, v33, v32
	v_readlane_b32 s9, v255, 32
	v_readlane_b32 s10, v255, 26
	v_cndmask_b32_e32 v33, v229, v33, vcc
	v_lshlrev_b32_e32 v38, 2, v33
	v_xor_b32_e32 v33, 4, v229
	v_cmp_lt_i32_e32 vcc, v33, v32
	v_cmp_eq_u32_e64 s[40:41], 0, v36
	s_mov_b32 s16, s10
	v_cndmask_b32_e32 v33, v229, v33, vcc
	v_lshlrev_b32_e32 v39, 2, v33
	v_xor_b32_e32 v33, 8, v229
	v_cmp_lt_i32_e32 vcc, v33, v32
	v_readlane_b32 s11, v255, 27
	s_nop 0
	v_cndmask_b32_e32 v33, v229, v33, vcc
	v_lshlrev_b32_e32 v40, 2, v33
	v_xor_b32_e32 v33, 16, v229
	v_cmp_lt_i32_e32 vcc, v33, v32
	s_nop 1
	v_cndmask_b32_e32 v33, v229, v33, vcc
	v_lshlrev_b32_e32 v41, 2, v33
	v_xor_b32_e32 v33, 32, v229
	v_cmp_lt_i32_e32 vcc, v33, v32
	s_nop 1
	v_cndmask_b32_e32 v32, v229, v33, vcc
	v_lshlrev_b32_e32 v42, 2, v32
	v_lshl_add_u64 v[32:33], s[8:9], 0, v[204:205]
	v_readlane_b32 s8, v255, 24
	v_readlane_b32 s9, v255, 25
	v_lshl_add_u64 v[192:193], v[32:33], 0, s[4:5]
	v_add_co_u32_e32 v194, vcc, s52, v192
	s_nop 1
	v_addc_co_u32_e32 v195, vcc, 0, v193, vcc
	v_add_co_u32_e32 v192, vcc, 0x39000000, v192
	s_nop 1
	v_addc_co_u32_e32 v193, vcc, 0, v193, vcc
	global_load_dwordx4 v[160:163], v[194:195], off
	global_load_dwordx4 v[164:167], v[194:195], off offset:1024
	global_load_dwordx4 v[168:171], v[194:195], off offset:2048
	global_load_dwordx4 v[172:175], v[194:195], off offset:3072
	global_load_dwordx4 v[176:179], v[192:193], off
	global_load_dwordx4 v[180:183], v[192:193], off offset:1024
	global_load_dwordx4 v[184:187], v[192:193], off offset:2048
	global_load_dwordx4 v[188:191], v[192:193], off offset:3072
	s_waitcnt vmcnt(0)
	s_branch .LBB0_791

; template <bool HIN_BF16, bool HOUT_BF16>
; __device__ __forceinline__ void norm_rows(const bf16* __restrict__ Y, const void* Hin, void* H, const float* __restrict__ gpost, float* __restrict__ RSout, int gw, int NGW, int lane) {
;     ...
;     for (int m = m0_; m < me_; m += ms_) {
;         f32x4 h[8];
;         if (HIN_BF16) {
; #pragma unroll
;             for (int j = 0; j < 4; ++j) { const v4u w = *(const v4u*)((const bf16*)Hin + (size_t)m * DM + 512 * j + 8 * lane);
;                 h[2 * j] = (f32x4){bf_lo(w[0]), bf_hi(w[0]), bf_lo(w[1]), bf_hi(w[1])}; h[2 * j + 1] = (f32x4){bf_lo(w[2]), bf_hi(w[2]), bf_lo(w[3]), bf_hi(w[3])}; }
;         } else {
;             const float* hr = (const float*)Hin + (size_t)m * DM + 8 * lane;
; #pragma unroll
;             for (int j = 0; j < 4; ++j) { h[2 * j] = *(const f32x4*)(hr + 512 * j); h[2 * j + 1] = *(const f32x4*)(hr + 512 * j + 4); }
;         }
;         if (Y) {
;             v4u y[4]; float ss = 0.f;
; #pragma unroll
;             for (int j = 0; j < 4; ++j) y[j] = *(const v4u*)(Y + (size_t)m * DM + 512 * j + 8 * lane);
; #pragma unroll
;             for (int j = 0; j < 4; ++j)
; #pragma unroll
;                 for (int e = 0; e < 4; ++e) { const float a = bf_lo(y[j][e]), b = bf_hi(y[j][e]); ss += a * a + b * b; }
;             const float rs = 1.0f / sqrtf(wave_sum(ss) * (1.0f / DM) + RMS_EPS);
.LBB0_791:
	v_lshl_add_u64 v[34:35], v[32:33], 0, s[4:5]
	v_add_co_u32_e32 v34, vcc, 0x39000000, v34
	s_nop 1
	v_addc_co_u32_e32 v35, vcc, 0, v35, vcc
	s_waitcnt lgkmcnt(0)
	s_waitcnt vmcnt(4)
	v_mov_b64_e32 v[44:45], v[160:161]
	v_mov_b64_e32 v[46:47], v[162:163]
	v_mov_b64_e32 v[48:49], v[164:165]
	v_mov_b64_e32 v[50:51], v[166:167]
	v_mov_b64_e32 v[52:53], v[168:169]
	v_mov_b64_e32 v[54:55], v[170:171]
	v_mov_b64_e32 v[56:57], v[172:173]
	v_mov_b64_e32 v[58:59], v[174:175]
	v_mov_b64_e32 v[60:61], v[176:177]
	v_mov_b64_e32 v[62:63], v[178:179]
	v_mov_b64_e32 v[64:65], v[180:181]
	v_mov_b64_e32 v[66:67], v[182:183]
	v_mov_b64_e32 v[68:69], v[184:185]
	v_mov_b64_e32 v[70:71], v[186:187]
	v_mov_b64_e32 v[72:73], v[188:189]
	v_mov_b64_e32 v[74:75], v[190:191]
	s_add_i32 s20, s16, s80
	s_cmp_lt_i32 s20, s96
	s_cbranch_scc0 .Ln2_nopf
	v_lshl_add_u64 v[192:193], v[32:33], 0, s[18:19]
	v_lshl_add_u64 v[192:193], v[192:193], 0, s[4:5]
	v_add_co_u32_e32 v194, vcc, s52, v192
	s_nop 1
	v_addc_co_u32_e32 v195, vcc, 0, v193, vcc
	v_add_co_u32_e32 v192, vcc, 0x39000000, v192
	s_nop 1
	v_addc_co_u32_e32 v193, vcc, 0, v193, vcc
	global_load_dwordx4 v[160:163], v[194:195], off
	global_load_dwordx4 v[164:167], v[194:195], off offset:1024
	global_load_dwordx4 v[168:171], v[194:195], off offset:2048
	global_load_dwordx4 v[172:175], v[194:195], off offset:3072
	global_load_dwordx4 v[176:179], v[192:193], off
	global_load_dwordx4 v[180:183], v[192:193], off offset:1024
	global_load_dwordx4 v[184:187], v[192:193], off offset:2048
	global_load_dwordx4 v[188:191], v[192:193], off offset:3072
.Ln2_nopf:
	v_lshlrev_b32_e32 v76, 16, v44
	v_and_b32_e32 v77, 0xffff0000, v44
	v_lshlrev_b32_e32 v44, 16, v45
	v_and_b32_e32 v45, 0xffff0000, v45
	v_and_b32_e32 v79, 0xffff0000, v46
	v_lshlrev_b32_e32 v92, 16, v60
	v_and_b32_e32 v93, 0xffff0000, v60
	v_mul_f32_e32 v43, v77, v77
	v_mul_f32_e32 v60, v45, v45
	v_lshlrev_b32_e32 v78, 16, v46
	v_lshlrev_b32_e32 v46, 16, v47
	v_and_b32_e32 v47, 0xffff0000, v47
	v_mul_f32_e32 v96, v79, v79
	v_fmac_f32_e32 v43, v76, v76
	v_fmac_f32_e32 v60, v44, v44
	v_and_b32_e32 v81, 0xffff0000, v48
	v_mul_f32_e32 v97, v47, v47
	v_fmac_f32_e32 v96, v78, v78
	v_add_f32_e32 v43, v43, v60
	v_lshlrev_b32_e32 v80, 16, v48
	v_lshlrev_b32_e32 v48, 16, v49
	v_and_b32_e32 v49, 0xffff0000, v49
	v_mul_f32_e32 v98, v81, v81
	v_fmac_f32_e32 v97, v46, v46
	v_add_f32_e32 v43, v96, v43
	v_and_b32_e32 v83, 0xffff0000, v50
	v_mul_f32_e32 v99, v49, v49
	v_fmac_f32_e32 v98, v80, v80
	v_add_f32_e32 v43, v97, v43
	v_lshlrev_b32_e32 v82, 16, v50
	v_lshlrev_b32_e32 v50, 16, v51
	v_and_b32_e32 v51, 0xffff0000, v51
	v_mul_f32_e32 v100, v83, v83
	v_fmac_f32_e32 v99, v48, v48
	v_add_f32_e32 v43, v98, v43
	v_and_b32_e32 v85, 0xffff0000, v52
	v_mul_f32_e32 v101, v51, v51
	v_fmac_f32_e32 v100, v82, v82
	v_add_f32_e32 v43, v99, v43
	v_lshlrev_b32_e32 v84, 16, v52
	v_lshlrev_b32_e32 v52, 16, v53
	v_and_b32_e32 v53, 0xffff0000, v53
	v_mul_f32_e32 v102, v85, v85
	v_fmac_f32_e32 v101, v50, v50
	v_add_f32_e32 v43, v100, v43
	v_and_b32_e32 v87, 0xffff0000, v54
	v_mul_f32_e32 v103, v53, v53
	v_fmac_f32_e32 v102, v84, v84
	v_add_f32_e32 v43, v101, v43
	v_lshlrev_b32_e32 v86, 16, v54
	v_lshlrev_b32_e32 v54, 16, v55
	v_and_b32_e32 v55, 0xffff0000, v55
	v_mul_f32_e32 v104, v87, v87
	v_fmac_f32_e32 v103, v52, v52
	v_add_f32_e32 v43, v102, v43
	v_and_b32_e32 v89, 0xffff0000, v56
	v_mul_f32_e32 v105, v55, v55
	v_fmac_f32_e32 v104, v86, v86
	v_add_f32_e32 v43, v103, v43
	v_lshlrev_b32_e32 v88, 16, v56
	v_lshlrev_b32_e32 v56, 16, v57
	v_and_b32_e32 v57, 0xffff0000, v57
	v_mul_f32_e32 v106, v89, v89
	v_fmac_f32_e32 v105, v54, v54
	v_add_f32_e32 v43, v104, v43
	v_lshlrev_b32_e32 v91, 16, v59
	v_lshlrev_b32_e32 v90, 16, v58
	v_and_b32_e32 v59, 0xffff0000, v59
	v_and_b32_e32 v58, 0xffff0000, v58
	v_mul_f32_e32 v107, v57, v57
	v_fmac_f32_e32 v106, v88, v88
	v_add_f32_e32 v43, v105, v43
	v_pk_mul_f32 v[94:95], v[58:59], v[58:59]
	v_fmac_f32_e32 v107, v56, v56
	v_add_f32_e32 v43, v106, v43
	v_pk_fma_f32 v[94:95], v[90:91], v[90:91], v[94:95]
	v_add_f32_e32 v43, v107, v43
	v_add_f32_e32 v43, v94, v43
	v_add_f32_e32 v43, v95, v43
	ds_bpermute_b32 v96, v37, v43
	v_and_b32_e32 v105, 0xffff0000, v72
	v_lshlrev_b32_e32 v60, 16, v61
	v_and_b32_e32 v61, 0xffff0000, v61
	v_pk_mul_f32 v[44:45], v[26:27], v[44:45]
	s_waitcnt lgkmcnt(0)
	v_add_f32_e32 v43, v43, v96
	ds_bpermute_b32 v98, v38, v43
	v_lshlrev_b32_e32 v94, 16, v62
	v_and_b32_e32 v95, 0xffff0000, v62
	v_lshlrev_b32_e32 v62, 16, v63
	v_and_b32_e32 v63, 0xffff0000, v63
	s_waitcnt lgkmcnt(0)
	v_add_f32_e32 v43, v43, v98
	ds_bpermute_b32 v100, v39, v43
	v_pk_mul_f32 v[46:47], v[2:3], v[46:47]
	v_lshlrev_b32_e32 v96, 16, v64
	v_and_b32_e32 v97, 0xffff0000, v64
	v_lshlrev_b32_e32 v64, 16, v65
	s_waitcnt lgkmcnt(0)
	v_add_f32_e32 v43, v43, v100
	ds_bpermute_b32 v102, v40, v43
	v_and_b32_e32 v65, 0xffff0000, v65
	v_lshlrev_b32_e32 v98, 16, v66
	v_and_b32_e32 v99, 0xffff0000, v66
	v_lshlrev_b32_e32 v66, 16, v67
	s_waitcnt lgkmcnt(0)
	v_add_f32_e32 v43, v43, v102
	ds_bpermute_b32 v104, v41, v43
	v_and_b32_e32 v67, 0xffff0000, v67
	v_lshlrev_b32_e32 v100, 16, v68
	v_and_b32_e32 v101, 0xffff0000, v68
	v_lshlrev_b32_e32 v68, 16, v69
	s_waitcnt lgkmcnt(0)
	v_add_f32_e32 v43, v43, v104
	ds_bpermute_b32 v106, v42, v43
	v_lshlrev_b32_e32 v104, 16, v72
	v_and_b32_e32 v69, 0xffff0000, v69
	v_lshlrev_b32_e32 v102, 16, v70
	v_and_b32_e32 v103, 0xffff0000, v70
	s_waitcnt lgkmcnt(0)
; __device__ __forceinline__ unsigned pk2(float lo, float hi) { return f2bf(lo) | (f2bf(hi) << 16); }
; template <bool HIN_BF16, bool HOUT_BF16>
; __device__ __forceinline__ void norm_rows(const bf16* __restrict__ Y, const void* Hin, void* H, const float* __restrict__ gpost, float* __restrict__ RSout, int gw, int NGW, int lane) {
;     ...
;             const float rs = 1.0f / sqrtf(wave_sum(ss) * (1.0f / DM) + RMS_EPS);
; #pragma unroll
;             for (int j = 0; j < 4; ++j) { const f32x4 g0 = *(const f32x4*)(gpost + 512 * j + 8 * lane), g1 = *(const f32x4*)(gpost + 512 * j + 8 * lane + 4);
;                 f32x4 a = {bf_lo(y[j][0]), bf_hi(y[j][0]), bf_lo(y[j][1]), bf_hi(y[j][1])}, b = {bf_lo(y[j][2]), bf_hi(y[j][2]), bf_lo(y[j][3]), bf_hi(y[j][3])};
;                 h[2 * j] = h[2 * j] + a * g0 * rs; h[2 * j + 1] = h[2 * j + 1] + b * g1 * rs; }
;         }
;         if (HOUT_BF16) {
; #pragma unroll
;             for (int j = 0; j < 4; ++j) { v4u w; w.x = pk2(h[2 * j][0], h[2 * j][1]); w.y = pk2(h[2 * j][2], h[2 * j][3]); w.z = pk2(h[2 * j + 1][0], h[2 * j + 1][1]); w.w = pk2(h[2 * j + 1][2], h[2 * j + 1][3]);
;                 *(v4u*)((bf16*)H + (size_t)m * DM + 512 * j + 8 * lane) = w; }
	v_add_f32_e32 v43, v43, v106
	v_fmamk_f32 v43, v43, 0x3a000000, v226
	v_mul_f32_e32 v72, 0x4f800000, v43
	v_cmp_gt_f32_e32 vcc, s93, v43
	v_lshlrev_b32_e32 v70, 16, v71
	v_and_b32_e32 v71, 0xffff0000, v71
	v_cndmask_b32_e32 v43, v43, v72, vcc
	v_sqrt_f32_e32 v107, v43
	v_lshlrev_b32_e32 v72, 16, v73
	v_and_b32_e32 v73, 0xffff0000, v73
	v_pk_mul_f32 v[76:77], v[24:25], v[76:77]
	v_add_u32_e32 v108, -1, v107
	v_fma_f32 v110, -v108, v107, v43
	v_add_u32_e32 v109, 1, v107
	v_cmp_ge_f32_e64 s[42:43], 0, v110
	v_lshlrev_b32_e32 v106, 16, v74
	s_nop 0
	v_cndmask_b32_e64 v108, v107, v108, s[42:43]
	v_fma_f32 v107, -v109, v107, v43
	v_cmp_lt_f32_e64 s[42:43], 0, v107
	s_nop 1
	v_cndmask_b32_e64 v107, v108, v109, s[42:43]
	v_mul_f32_e32 v108, 0x37800000, v107
	v_cndmask_b32_e32 v107, v107, v108, vcc
	v_cmp_class_f32_e32 vcc, v43, v227
	s_nop 1
	v_cndmask_b32_e32 v43, v107, v43, vcc
	v_div_scale_f32 v108, s[10:11], v43, v43, 1.0
	v_rcp_f32_e32 v109, v108
	v_and_b32_e32 v107, 0xffff0000, v74
	v_lshlrev_b32_e32 v74, 16, v75
	v_and_b32_e32 v75, 0xffff0000, v75
	v_fma_f32 v110, -v108, v109, 1.0
	v_fmac_f32_e32 v109, v110, v109
	v_div_scale_f32 v110, vcc, 1.0, v43, 1.0
	v_mul_f32_e32 v111, v110, v109
	v_fma_f32 v112, -v108, v111, v110
	v_fmac_f32_e32 v111, v112, v109
	v_fma_f32 v108, -v108, v111, v110
	v_div_fmas_f32 v108, v108, v109, v111
	v_div_fixup_f32 v108, v108, v43, 1.0
	v_pk_fma_f32 v[60:61], v[44:45], v[108:109], v[60:61] op_sel_hi:[1,0,1]
	v_pk_mul_f32 v[44:45], v[0:1], v[78:79]
	v_pk_fma_f32 v[62:63], v[46:47], v[108:109], v[62:63] op_sel_hi:[1,0,1]
	v_pk_fma_f32 v[78:79], v[44:45], v[108:109], v[94:95] op_sel_hi:[1,0,1]
	v_pk_mul_f32 v[44:45], v[4:5], v[80:81]
	v_pk_mul_f32 v[46:47], v[6:7], v[48:49]
	v_pk_fma_f32 v[76:77], v[76:77], v[108:109], v[92:93] op_sel_hi:[1,0,1]
	v_pk_fma_f32 v[48:49], v[46:47], v[108:109], v[64:65] op_sel_hi:[1,0,1]
	v_pk_fma_f32 v[64:65], v[44:45], v[108:109], v[96:97] op_sel_hi:[1,0,1]
	v_pk_mul_f32 v[44:45], v[8:9], v[82:83]
	v_pk_mul_f32 v[46:47], v[10:11], v[50:51]
	v_bfe_u32 v43, v76, 16, 1
	v_pk_fma_f32 v[50:51], v[46:47], v[108:109], v[66:67] op_sel_hi:[1,0,1]
	v_pk_fma_f32 v[66:67], v[44:45], v[108:109], v[98:99] op_sel_hi:[1,0,1]
	v_pk_mul_f32 v[44:45], v[16:17], v[84:85]
	v_pk_mul_f32 v[46:47], v[18:19], v[52:53]
	v_add3_u32 v43, v76, v43, s56
	v_pk_fma_f32 v[52:53], v[46:47], v[108:109], v[68:69] op_sel_hi:[1,0,1]
	v_pk_fma_f32 v[68:69], v[44:45], v[108:109], v[100:101] op_sel_hi:[1,0,1]
	v_pk_mul_f32 v[44:45], v[12:13], v[86:87]
	v_pk_mul_f32 v[46:47], v[14:15], v[54:55]
	v_lshrrev_b32_e32 v43, 16, v43
	v_pk_fma_f32 v[54:55], v[46:47], v[108:109], v[70:71] op_sel_hi:[1,0,1]
	v_pk_fma_f32 v[70:71], v[44:45], v[108:109], v[102:103] op_sel_hi:[1,0,1]
	v_pk_mul_f32 v[44:45], v[20:21], v[88:89]
	v_pk_mul_f32 v[46:47], v[22:23], v[56:57]
	s_nop 0
	v_pk_fma_f32 v[56:57], v[46:47], v[108:109], v[72:73] op_sel_hi:[1,0,1]
	v_pk_fma_f32 v[72:73], v[44:45], v[108:109], v[104:105] op_sel_hi:[1,0,1]
	v_mov_b32_e32 v44, v90
	v_mov_b32_e32 v45, v58
	v_mov_b32_e32 v58, v91
	v_pk_mul_f32 v[44:45], v[28:29], v[44:45]
	v_pk_mul_f32 v[46:47], v[30:31], v[58:59]
	s_nop 0
	v_pk_fma_f32 v[58:59], v[46:47], v[108:109], v[74:75] op_sel_hi:[1,0,1]
	v_pk_fma_f32 v[74:75], v[44:45], v[108:109], v[106:107] op_sel_hi:[1,0,1]
	v_bfe_u32 v44, v77, 16, 1
	v_add3_u32 v44, v77, v44, s56
	v_and_or_b32 v44, v44, s82, v43
	v_bfe_u32 v43, v60, 16, 1
	v_add3_u32 v43, v60, v43, s56
	v_bfe_u32 v45, v61, 16, 1
	v_lshrrev_b32_e32 v43, 16, v43
	v_add3_u32 v45, v61, v45, s56
	v_and_or_b32 v45, v45, s82, v43
	v_bfe_u32 v43, v78, 16, 1
	v_add3_u32 v43, v78, v43, s56
	v_bfe_u32 v46, v79, 16, 1
	v_lshrrev_b32_e32 v43, 16, v43
	v_add3_u32 v46, v79, v46, s56
	v_and_or_b32 v46, v46, s82, v43
	v_bfe_u32 v43, v62, 16, 1
	v_add3_u32 v43, v62, v43, s56
	v_bfe_u32 v47, v63, 16, 1
	v_lshrrev_b32_e32 v43, 16, v43
	v_add3_u32 v47, v63, v47, s56
	v_and_or_b32 v47, v47, s82, v43
	v_bfe_u32 v43, v64, 16, 1
	global_store_dwordx4 v[34:35], v[44:47], off
	v_add3_u32 v43, v64, v43, s56
	v_lshrrev_b32_e32 v43, 16, v43
	v_bfe_u32 v44, v65, 16, 1
	v_add3_u32 v44, v65, v44, s56
	v_and_or_b32 v44, v44, s82, v43
	v_bfe_u32 v43, v48, 16, 1
	v_add3_u32 v43, v48, v43, s56
	v_bfe_u32 v45, v49, 16, 1
	v_lshrrev_b32_e32 v43, 16, v43
	v_add3_u32 v45, v49, v45, s56
	v_and_or_b32 v45, v45, s82, v43
	v_bfe_u32 v43, v66, 16, 1
	v_add3_u32 v43, v66, v43, s56
	v_bfe_u32 v46, v67, 16, 1
	v_lshrrev_b32_e32 v43, 16, v43
	v_add3_u32 v46, v67, v46, s56
	v_and_or_b32 v46, v46, s82, v43
	v_bfe_u32 v43, v50, 16, 1
	v_add3_u32 v43, v50, v43, s56
	v_bfe_u32 v47, v51, 16, 1
	v_lshrrev_b32_e32 v43, 16, v43
	v_add3_u32 v47, v51, v47, s56
	v_and_or_b32 v47, v47, s82, v43
; __device__ __forceinline__ unsigned pk2(float lo, float hi) { return f2bf(lo) | (f2bf(hi) << 16); }
; template <bool HIN_BF16, bool HOUT_BF16>
; __device__ __forceinline__ void norm_rows(const bf16* __restrict__ Y, const void* Hin, void* H, const float* __restrict__ gpost, float* __restrict__ RSout, int gw, int NGW, int lane) {
;     ...
;         if (HOUT_BF16) {
; #pragma unroll
;             for (int j = 0; j < 4; ++j) { v4u w; w.x = pk2(h[2 * j][0], h[2 * j][1]); w.y = pk2(h[2 * j][2], h[2 * j][3]); w.z = pk2(h[2 * j + 1][0], h[2 * j + 1][1]); w.w = pk2(h[2 * j + 1][2], h[2 * j + 1][3]);
;                 *(v4u*)((bf16*)H + (size_t)m * DM + 512 * j + 8 * lane) = w; }
;         } else { float* ho = (float*)H + (size_t)m * DM + 8 * lane;
; #pragma unroll
;             for (int j = 0; j < 4; ++j) { *(f32x4*)(ho + 512 * j) = h[2 * j]; *(f32x4*)(ho + 512 * j + 4) = h[2 * j + 1]; } }
;         if (RSout) {
;             float ss = 0.f;
; #pragma unroll
;             for (int j = 0; j < 8; ++j) ss += (h[j][0] * h[j][0] + h[j][1] * h[j][1]) + (h[j][2] * h[j][2] + h[j][3] * h[j][3]);
;             const float rs = 1.0f / sqrtf(wave_sum(ss) * (1.0f / DM) + RMS_EPS);
;             if (lane == 0) RSout[m] = rs;
;         }
	v_bfe_u32 v43, v68, 16, 1
	global_store_dwordx4 v[34:35], v[44:47], off offset:1024
	v_add3_u32 v43, v68, v43, s56
	v_lshrrev_b32_e32 v43, 16, v43
	v_bfe_u32 v44, v69, 16, 1
	v_add3_u32 v44, v69, v44, s56
	v_and_or_b32 v44, v44, s82, v43
	v_bfe_u32 v43, v52, 16, 1
	v_add3_u32 v43, v52, v43, s56
	v_bfe_u32 v45, v53, 16, 1
	v_lshrrev_b32_e32 v43, 16, v43
	v_add3_u32 v45, v53, v45, s56
	v_and_or_b32 v45, v45, s82, v43
	v_bfe_u32 v43, v70, 16, 1
	v_add3_u32 v43, v70, v43, s56
	v_bfe_u32 v46, v71, 16, 1
	v_lshrrev_b32_e32 v43, 16, v43
	v_add3_u32 v46, v71, v46, s56
	v_and_or_b32 v46, v46, s82, v43
	v_bfe_u32 v43, v54, 16, 1
	v_add3_u32 v43, v54, v43, s56
	v_bfe_u32 v47, v55, 16, 1
	v_lshrrev_b32_e32 v43, 16, v43
	v_add3_u32 v47, v55, v47, s56
	v_and_or_b32 v47, v47, s82, v43
	global_store_dwordx4 v[34:35], v[44:47], off offset:2048
	v_bfe_u32 v43, v72, 16, 1
	v_add3_u32 v43, v72, v43, s56
	v_mul_f32_e32 v44, v77, v77
	v_mul_f32_e32 v45, v61, v61
	v_fmac_f32_e32 v44, v76, v76
	v_fmac_f32_e32 v45, v60, v60
	v_add_f32_e32 v44, v44, v45
	v_mul_f32_e32 v45, v79, v79
	v_mul_f32_e32 v46, v63, v63
	v_fmac_f32_e32 v45, v78, v78
	v_fmac_f32_e32 v46, v62, v62
	v_add_f32_e32 v45, v45, v46
	v_add_f32_e32 v44, v44, v45
	v_mul_f32_e32 v45, v65, v65
	v_mul_f32_e32 v46, v49, v49
	v_fmac_f32_e32 v45, v64, v64
	v_fmac_f32_e32 v46, v48, v48
	v_add_f32_e32 v45, v45, v46
	v_add_f32_e32 v44, v45, v44
	v_mul_f32_e32 v45, v67, v67
	v_mul_f32_e32 v46, v51, v51
	v_fmac_f32_e32 v45, v66, v66
	v_fmac_f32_e32 v46, v50, v50
	v_add_f32_e32 v45, v45, v46
	v_add_f32_e32 v44, v45, v44
	v_mul_f32_e32 v45, v69, v69
	v_mul_f32_e32 v46, v53, v53
	v_fmac_f32_e32 v45, v68, v68
	v_fmac_f32_e32 v46, v52, v52
	v_add_f32_e32 v45, v45, v46
	v_add_f32_e32 v44, v45, v44
	v_mul_f32_e32 v45, v71, v71
	v_mul_f32_e32 v46, v55, v55
	v_fmac_f32_e32 v45, v70, v70
	v_fmac_f32_e32 v46, v54, v54
	v_add_f32_e32 v45, v45, v46
	v_add_f32_e32 v44, v45, v44
	v_mul_f32_e32 v45, v73, v73
	v_mul_f32_e32 v46, v57, v57
	v_fmac_f32_e32 v45, v72, v72
	v_fmac_f32_e32 v46, v56, v56
	v_add_f32_e32 v45, v45, v46
	v_add_f32_e32 v44, v45, v44
	v_mul_f32_e32 v45, v75, v75
	v_mul_f32_e32 v46, v59, v59
	v_fmac_f32_e32 v45, v74, v74
	v_fmac_f32_e32 v46, v58, v58
	v_add_f32_e32 v45, v45, v46
	v_add_f32_e32 v44, v45, v44
	ds_bpermute_b32 v45, v37, v44
	v_bfe_u32 v46, v73, 16, 1
	v_lshrrev_b32_e32 v43, 16, v43
	v_add3_u32 v46, v73, v46, s56
	v_and_or_b32 v46, v46, s82, v43
	s_waitcnt lgkmcnt(0)
	v_add_f32_e32 v44, v44, v45
	ds_bpermute_b32 v45, v38, v44
	v_bfe_u32 v43, v56, 16, 1
	v_add3_u32 v43, v56, v43, s56
	v_bfe_u32 v47, v57, 16, 1
	v_lshrrev_b32_e32 v43, 16, v43
	s_waitcnt lgkmcnt(0)
	v_add_f32_e32 v44, v44, v45
	ds_bpermute_b32 v45, v39, v44
	v_add3_u32 v47, v57, v47, s56
	v_and_or_b32 v47, v47, s82, v43
	v_bfe_u32 v43, v74, 16, 1
	v_add3_u32 v43, v74, v43, s56
	s_waitcnt lgkmcnt(0)
	v_add_f32_e32 v44, v44, v45
	ds_bpermute_b32 v45, v40, v44
	v_bfe_u32 v48, v75, 16, 1
	v_lshrrev_b32_e32 v43, 16, v43
	v_add3_u32 v48, v75, v48, s56
	v_and_or_b32 v48, v48, s82, v43
	s_waitcnt lgkmcnt(0)
	v_add_f32_e32 v44, v44, v45
	ds_bpermute_b32 v45, v41, v44
	v_bfe_u32 v43, v58, 16, 1
	v_add3_u32 v43, v58, v43, s56
	v_lshrrev_b32_e32 v49, 16, v43
	s_waitcnt lgkmcnt(0)
	v_add_f32_e32 v43, v44, v45
	ds_bpermute_b32 v44, v42, v43
	v_bfe_u32 v45, v59, 16, 1
	v_add3_u32 v45, v59, v45, s56
	v_and_or_b32 v49, v45, s82, v49
	global_store_dwordx4 v[34:35], v[46:49], off offset:3072
	s_and_saveexec_b64 s[10:11], s[40:41]
	s_cbranch_execz .LBB0_790
	s_waitcnt lgkmcnt(0)
	v_add_f32_e32 v34, v43, v44
	v_fmamk_f32 v34, v34, 0x3a000000, v226
	v_mul_f32_e32 v35, 0x4f800000, v34
	v_cmp_gt_f32_e32 vcc, s93, v34
	s_nop 1
	v_cndmask_b32_e32 v34, v34, v35, vcc
	v_sqrt_f32_e32 v35, v34
	s_nop 0
	v_add_u32_e32 v43, -1, v35
	v_fma_f32 v45, -v43, v35, v34
	v_add_u32_e32 v44, 1, v35
	v_cmp_ge_f32_e64 s[42:43], 0, v45
	s_nop 1
	v_cndmask_b32_e64 v43, v35, v43, s[42:43]
	v_fma_f32 v35, -v44, v35, v34
	v_cmp_lt_f32_e64 s[42:43], 0, v35
	s_nop 1
	v_cndmask_b32_e64 v35, v43, v44, s[42:43]
	v_mul_f32_e32 v43, 0x37800000, v35
	v_cndmask_b32_e32 v35, v35, v43, vcc
	v_cmp_class_f32_e32 vcc, v34, v227
	s_nop 1
	v_cndmask_b32_e32 v34, v35, v34, vcc
	v_div_scale_f32 v35, s[20:21], v34, v34, 1.0
	v_rcp_f32_e32 v43, v35
	s_add_u32 s20, s8, s4
	s_addc_u32 s21, s9, s5
	v_fma_f32 v44, -v35, v43, 1.0
	v_fmac_f32_e32 v43, v44, v43
	v_div_scale_f32 v44, vcc, 1.0, v34, 1.0
	v_mul_f32_e32 v45, v44, v43
	v_fma_f32 v46, -v35, v45, v44
	v_fmac_f32_e32 v45, v46, v43
	v_fma_f32 v35, -v35, v45, v44
	v_div_fmas_f32 v35, v35, v43, v45
	v_div_fixup_f32 v34, v35, v34, 1.0
	global_store_dword v205, v34, s[20:21]
	s_branch .LBB0_790
